# phase B2: all 17 loads of a token issued before one wait (own destination register per bf16 load) instead of five serialized groups
# speedup vs baseline: 1.1903x; 1.0035x over previous
.LBB0_809:
	v_cmp_gt_i32_e32 vcc, s37, v6
	s_mov_b32 s0, 0xd0a3000
	v_ashrrev_i32_e32 v15, 31, v14
	v_cndmask_b32_e32 v2, v213, v214, vcc
	v_and_b32_e32 v16, v2, v6
	v_ashrrev_i32_e32 v17, 31, v16
	v_lshlrev_b64 v[22:23], 2, v[16:17]
	v_lshl_add_u64 v[16:17], s[18:19], 0, v[12:13]
	v_add_co_u32_e64 v36, s[0:1], s0, v16
	v_cndmask_b32_e32 v7, v215, v216, vcc
	s_nop 0
	v_addc_co_u32_e64 v37, s[0:1], 0, v17, s[0:1]
	s_mov_b32 s0, 0xd8a3000
	v_and_or_b32 v22, v7, v6, v22
	v_add_co_u32_e64 v40, s[0:1], s0, v16
	v_lshl_add_u64 v[2:3], v[14:15], 2, s[52:53]
	s_nop 0
	v_addc_co_u32_e64 v41, s[0:1], 0, v17, s[0:1]
	v_mad_u64_u32 v[16:17], s[0:1], v22, s66, v[8:9]
	v_mad_i32_i24 v17, v23, s66, v17
	global_load_dwordx4 v[2:5], v[2:3], off
	s_mov_b32 s0, 0x78a3000
	global_load_dword v39, v[36:37], off offset:1792 nt
	global_load_dword v43, v[40:41], off offset:1792 nt
	global_load_dword v48, v[16:17], off
	v_lshl_add_u64 v[16:17], s[18:19], 0, v[10:11]
	v_add_co_u32_e64 v44, s[0:1], s0, v16
	v_add_u32_e32 v6, s10, v6
	s_nop 0
	v_addc_co_u32_e64 v45, s[0:1], 0, v17, s[0:1]
	global_load_ushort v49, v[44:45], off offset:2304
	global_load_dword v38, v[36:37], off offset:2048 nt
	global_load_dword v42, v[40:41], off offset:2048 nt
	v_lshl_add_u64 v[10:11], v[10:11], 0, s[62:63]
	v_lshl_add_u64 v[12:13], v[12:13], 0, s[12:13]
	v_add_u32_e32 v14, s11, v14
	v_cndmask_b32_e64 v52, 10, 8, vcc
	v_lshlrev_b64 v[18:19], v52, 1
	v_lshl_add_u64 v[18:19], v[22:23], 0, v[18:19]
	v_mad_u64_u32 v[20:21], s[0:1], v18, s66, v[8:9]
	v_mad_i32_i24 v21, v19, s66, v21
	global_load_dword v50, v[20:21], off
	global_load_ushort v51, v[44:45], off offset:2432
	v_lshlrev_b64 v[34:35], v52, 2
	v_lshl_add_u64 v[34:35], v[22:23], 0, v[34:35]
	v_mad_u64_u32 v[46:47], s[0:1], v34, s66, v[8:9]
	v_mad_i32_i24 v47, v35, s66, v47
	global_load_dword v19, v[36:37], off offset:2304 nt
	global_load_dword v21, v[40:41], off offset:2304 nt
	global_load_dword v33, v[46:47], off
	global_load_ushort v34, v[44:45], off offset:2560
	global_load_dword v18, v[36:37], off offset:2560 nt
	global_load_dword v20, v[40:41], off offset:2560 nt
	v_lshlrev_b64 v[36:37], v52, 3
	v_lshl_add_u64 v[22:23], v[22:23], 0, v[36:37]
	v_mad_u64_u32 v[36:37], s[0:1], v22, s66, v[8:9]
	v_mad_i32_i24 v37, v23, s66, v37
	s_mov_b32 s0, 0x3a27c5ac
	global_load_dword v7, v[36:37], off
	global_load_ushort v15, v[44:45], off offset:2688
	v_mov_b32_e32 v37, v131
	v_mov_b32_e32 v36, v131
	s_waitcnt vmcnt(0)
	v_lshlrev_b32_e32 v15, 16, v15
	v_lshlrev_b32_e32 v49, 16, v49
	v_lshlrev_b32_e32 v51, 16, v51
	v_lshlrev_b32_e32 v34, 16, v34
	v_pk_add_f32 v[22:23], v[38:39], v[42:43]
	v_mov_b32_e32 v39, v131
	v_mov_b32_e32 v38, v131
	v_mov_b32_dpp v37, v23 row_ror:8 row_mask:0xf bank_mask:0xf
	v_mov_b32_dpp v36, v22 row_ror:8 row_mask:0xf bank_mask:0xf
	v_pk_add_f32 v[36:37], v[22:23], v[36:37]
	s_nop 1
	v_mov_b32_dpp v39, v37 row_ror:4 row_mask:0xf bank_mask:0xf
	v_mov_b32_dpp v38, v36 row_ror:4 row_mask:0xf bank_mask:0xf
	v_pk_add_f32 v[36:37], v[36:37], v[38:39]
	v_mov_b32_e32 v39, v131
	v_mov_b32_e32 v38, v131
	s_nop 0
	v_mov_b32_dpp v39, v37 row_ror:2 row_mask:0xf bank_mask:0xf
	v_mov_b32_dpp v38, v36 row_ror:2 row_mask:0xf bank_mask:0xf
	v_pk_add_f32 v[36:37], v[36:37], v[38:39]
	v_mov_b32_e32 v39, v131
	v_mov_b32_e32 v38, v131
	s_nop 0
	v_mov_b32_dpp v39, v37 row_ror:1 row_mask:0xf bank_mask:0xf
	v_mov_b32_dpp v38, v36 row_ror:1 row_mask:0xf bank_mask:0xf
	v_pk_add_f32 v[36:37], v[36:37], v[38:39]
	ds_bpermute_b32 v39, v31, v37
	ds_bpermute_b32 v38, v31, v36
	s_waitcnt lgkmcnt(0)
	v_pk_add_f32 v[36:37], v[36:37], v[38:39]
	ds_bpermute_b32 v39, v32, v37
	ds_bpermute_b32 v38, v32, v36
	s_waitcnt lgkmcnt(0)
	v_pk_add_f32 v[36:37], v[36:37], v[38:39]
	s_nop 0
	v_pk_fma_f32 v[36:37], v[36:37], s[14:15], v[22:23] op_sel_hi:[1,0,1] neg_lo:[1,0,0] neg_hi:[1,0,0]
	v_mov_b32_e32 v39, v131
	v_pk_mul_f32 v[22:23], v[36:37], v[36:37]
	v_mov_b32_e32 v38, v131
	s_nop 0
	v_mov_b32_dpp v39, v23 row_ror:8 row_mask:0xf bank_mask:0xf
	v_mov_b32_dpp v38, v22 row_ror:8 row_mask:0xf bank_mask:0xf
	v_pk_fma_f32 v[22:23], v[36:37], v[36:37], v[38:39]
	v_mov_b32_e32 v39, v131
	v_mov_b32_e32 v38, v131
	s_nop 0
	v_mov_b32_dpp v39, v23 row_ror:4 row_mask:0xf bank_mask:0xf
	v_mov_b32_dpp v38, v22 row_ror:4 row_mask:0xf bank_mask:0xf
	v_pk_add_f32 v[22:23], v[22:23], v[38:39]
	v_mov_b32_e32 v39, v131
	v_mov_b32_e32 v38, v131
	s_nop 0
	v_mov_b32_dpp v39, v23 row_ror:2 row_mask:0xf bank_mask:0xf
	v_mov_b32_dpp v38, v22 row_ror:2 row_mask:0xf bank_mask:0xf
	v_pk_add_f32 v[22:23], v[22:23], v[38:39]
	v_mov_b32_e32 v39, v131
	v_mov_b32_e32 v38, v131
	s_nop 0
	v_mov_b32_dpp v39, v23 row_ror:1 row_mask:0xf bank_mask:0xf
	v_mov_b32_dpp v38, v22 row_ror:1 row_mask:0xf bank_mask:0xf
	v_pk_add_f32 v[22:23], v[22:23], v[38:39]
	ds_bpermute_b32 v39, v31, v23
	ds_bpermute_b32 v38, v31, v22
	s_waitcnt lgkmcnt(0)
	v_pk_add_f32 v[22:23], v[22:23], v[38:39]
	ds_bpermute_b32 v39, v32, v23
	ds_bpermute_b32 v38, v32, v22
	s_waitcnt lgkmcnt(0)
	v_pk_add_f32 v[38:39], v[22:23], v[38:39]
	v_mov_b64_e32 v[22:23], s[0:1]
	v_pk_fma_f32 v[38:39], v[38:39], s[14:15], v[22:23] op_sel_hi:[1,0,0]
	s_nop 0
	v_mul_f32_e32 v35, 0x4b800000, v39
	v_cmp_gt_f32_e64 s[0:1], s50, v39
	v_cmp_gt_f32_e32 vcc, s50, v38
	s_nop 0
	v_cndmask_b32_e64 v35, v39, v35, s[0:1]
	v_rsq_f32_e32 v35, v35
	s_nop 0
	v_mul_f32_e32 v39, 0x45800000, v35
	v_cndmask_b32_e64 v35, v35, v39, s[0:1]
	v_mul_f32_e32 v35, v37, v35
	v_fma_f32 v35, v1, v35, v27
	v_fmac_f32_e32 v35, v2, v48
	v_mul_f32_e32 v2, v35, v49
	v_add_co_u32_e64 v16, s[0:1], s49, v16
	v_cvt_pk_bf16_f32 v2, v2, v131
	s_nop 1
	v_addc_co_u32_e64 v17, s[0:1], 0, v17, s[0:1]
	global_store_short v[16:17], v2, off offset:2304
	v_mul_f32_e32 v2, 0x4b800000, v38
	v_cndmask_b32_e32 v2, v38, v2, vcc
	v_rsq_f32_e32 v2, v2
	s_nop 0
	v_mul_f32_e32 v35, 0x45800000, v2
	v_cndmask_b32_e32 v2, v2, v35, vcc
	v_mul_f32_e32 v2, v36, v2
	v_fma_f32 v2, v24, v2, v28
	v_fmac_f32_e32 v2, v3, v50
	v_mul_f32_e32 v2, v2, v51
	v_cvt_pk_bf16_f32 v2, v2, v131
	global_store_short v[16:17], v2, off offset:2432
	v_pk_add_f32 v[2:3], v[18:19], v[20:21]
	v_mov_b32_e32 v19, v131
	v_mov_b32_e32 v18, v131
	v_mov_b32_e32 v21, v131
	v_mov_b32_dpp v19, v3 row_ror:8 row_mask:0xf bank_mask:0xf
	v_mov_b32_dpp v18, v2 row_ror:8 row_mask:0xf bank_mask:0xf
	v_pk_add_f32 v[18:19], v[2:3], v[18:19]
	v_mov_b32_e32 v20, v131
	s_nop 0
	v_mov_b32_dpp v21, v19 row_ror:4 row_mask:0xf bank_mask:0xf
	v_mov_b32_dpp v20, v18 row_ror:4 row_mask:0xf bank_mask:0xf
	v_pk_add_f32 v[18:19], v[18:19], v[20:21]
	v_mov_b32_e32 v21, v131
	v_mov_b32_e32 v20, v131
	s_nop 0
	v_mov_b32_dpp v21, v19 row_ror:2 row_mask:0xf bank_mask:0xf
	v_mov_b32_dpp v20, v18 row_ror:2 row_mask:0xf bank_mask:0xf
	v_pk_add_f32 v[18:19], v[18:19], v[20:21]
	v_mov_b32_e32 v21, v131
	v_mov_b32_e32 v20, v131
	s_nop 0
	v_mov_b32_dpp v21, v19 row_ror:1 row_mask:0xf bank_mask:0xf
	v_mov_b32_dpp v20, v18 row_ror:1 row_mask:0xf bank_mask:0xf
	v_pk_add_f32 v[18:19], v[18:19], v[20:21]
	ds_bpermute_b32 v21, v31, v19
	ds_bpermute_b32 v20, v31, v18
	s_waitcnt lgkmcnt(0)
	v_pk_add_f32 v[18:19], v[18:19], v[20:21]
	ds_bpermute_b32 v21, v32, v19
	ds_bpermute_b32 v20, v32, v18
	s_waitcnt lgkmcnt(0)
	v_pk_add_f32 v[18:19], v[18:19], v[20:21]
	s_nop 0
	v_pk_fma_f32 v[2:3], v[18:19], s[14:15], v[2:3] op_sel_hi:[1,0,1] neg_lo:[1,0,0] neg_hi:[1,0,0]
	v_mov_b32_e32 v21, v131
	v_pk_mul_f32 v[18:19], v[2:3], v[2:3]
	v_mov_b32_e32 v20, v131
	s_nop 0
	v_mov_b32_dpp v21, v19 row_ror:8 row_mask:0xf bank_mask:0xf
	v_mov_b32_dpp v20, v18 row_ror:8 row_mask:0xf bank_mask:0xf
	v_pk_fma_f32 v[18:19], v[2:3], v[2:3], v[20:21]
	v_mov_b32_e32 v21, v131
	v_mov_b32_e32 v20, v131
	s_nop 0
	v_mov_b32_dpp v21, v19 row_ror:4 row_mask:0xf bank_mask:0xf
	v_mov_b32_dpp v20, v18 row_ror:4 row_mask:0xf bank_mask:0xf
	v_pk_add_f32 v[18:19], v[18:19], v[20:21]
	v_mov_b32_e32 v21, v131
	v_mov_b32_e32 v20, v131
	s_nop 0
	v_mov_b32_dpp v21, v19 row_ror:2 row_mask:0xf bank_mask:0xf
	v_mov_b32_dpp v20, v18 row_ror:2 row_mask:0xf bank_mask:0xf
	v_pk_add_f32 v[18:19], v[18:19], v[20:21]
	v_mov_b32_e32 v21, v131
	v_mov_b32_e32 v20, v131
	s_nop 0
	v_mov_b32_dpp v21, v19 row_ror:1 row_mask:0xf bank_mask:0xf
	v_mov_b32_dpp v20, v18 row_ror:1 row_mask:0xf bank_mask:0xf
	v_pk_add_f32 v[18:19], v[18:19], v[20:21]
	ds_bpermute_b32 v21, v31, v19
	ds_bpermute_b32 v20, v31, v18
	s_waitcnt lgkmcnt(0)
	v_pk_add_f32 v[18:19], v[18:19], v[20:21]
	ds_bpermute_b32 v21, v32, v19
	ds_bpermute_b32 v20, v32, v18
	s_waitcnt lgkmcnt(0)
	v_pk_add_f32 v[18:19], v[18:19], v[20:21]
	s_nop 0
	v_pk_fma_f32 v[18:19], v[18:19], s[14:15], v[22:23] op_sel_hi:[1,0,0]
	s_nop 0
	v_mul_f32_e32 v20, 0x4b800000, v19
	v_cmp_gt_f32_e64 s[0:1], s50, v19
	v_cmp_gt_f32_e32 vcc, s50, v18
	s_nop 0
	v_cndmask_b32_e64 v19, v19, v20, s[0:1]
	v_rsq_f32_e32 v19, v19
	s_nop 0
	v_mul_f32_e32 v20, 0x45800000, v19
	v_cndmask_b32_e64 v19, v19, v20, s[0:1]
	v_mul_f32_e32 v3, v3, v19
	v_fma_f32 v3, v25, v3, v29
	v_fmac_f32_e32 v3, v4, v33
	v_mul_f32_e32 v3, v3, v34
	v_cvt_pk_bf16_f32 v3, v3, v131
	global_store_short v[16:17], v3, off offset:2560
	v_mul_f32_e32 v3, 0x4b800000, v18
	v_cndmask_b32_e32 v3, v18, v3, vcc
	v_rsq_f32_e32 v3, v3
	s_movk_i32 s0, 0x1fff
	v_mul_f32_e32 v4, 0x45800000, v3
	v_cndmask_b32_e32 v3, v3, v4, vcc
	v_mul_f32_e32 v2, v2, v3
	v_fma_f32 v2, v26, v2, v30
	v_fmac_f32_e32 v2, v5, v7
	v_cmp_lt_i32_e32 vcc, s0, v6
	v_mul_f32_e32 v2, v2, v15
	s_or_b64 s[6:7], vcc, s[6:7]
	v_cvt_pk_bf16_f32 v2, v2, v131
	global_store_short v[16:17], v2, off offset:2688
	s_andn2_b64 exec, exec, s[6:7]
	s_cbranch_execnz .LBB0_809
